# seven per-XCD barriers per layer (H1, H3 and xattn units remapped to the XCD owning their rows), three write-back-free ordering barriers; all guarded by the run-time dispatch check
# speedup vs baseline: 1.0121x; 1.0050x over previous
; __device__ __forceinline__ unsigned xb_add(unsigned* p, unsigned v) { return __hip_atomic_fetch_add(p, v, __ATOMIC_RELAXED, __HIP_MEMORY_SCOPE_AGENT); }
; __device__ __forceinline__ void xcd_barrier(const XcdBarrier& b) {
;     ...
;         const unsigned old = xb_add(&bar[XB_XSUB(b.x)], 1u);
;         const unsigned gen = old / nloc;
;         if (old + 1u == (gen + 1u) * nloc) {
;             __builtin_amdgcn_fence(__ATOMIC_RELEASE, "agent");
;             asm volatile("s_waitcnt vmcnt(0)" ::: "memory");
;             const unsigned og = xb_add(&bar[XB_TOP], 1u);
.LBB0_296:
	s_andn2_saveexec_b64 s[2:3], s[2:3]
	s_cbranch_execz .LBB0_314
	s_mov_b64 s[2:3], exec
	s_cmp_lg_u32 s101, 0
	s_cbranch_scc0 .Lnowb_2
	buffer_wbl2 sc1
.Lnowb_2:
	s_waitcnt lgkmcnt(0)
	s_waitcnt vmcnt(0)
	v_mbcnt_lo_u32_b32 v0, s2, 0
	v_mbcnt_hi_u32_b32 v0, s3, v0
	v_cmp_eq_u32_e32 vcc, 0, v0
	s_and_saveexec_b64 s[4:5], vcc
	s_cbranch_execz .LBB0_299
	s_bcnt1_i32_b64 s2, s[2:3]
	v_mov_b32_e32 v3, s2
	v_readlane_b32 s2, v253, 52
	v_readlane_b32 s3, v253, 53
	s_nop 4
	global_atomic_add v3, v1, v3, s[2:3] sc0

; DI void hgrn3_phase(bf16* Z2, const unsigned long long* OI, const float* gain, int gw, int NGW, int lane) {
;     const int fr = lane & 15, fq = lane >> 4;
;     for (int it = gw; it < 2048 * 4; it += NGW) {
;         const int unit = it >> 2, tt = it & 3, c = unit & 63, h = (unit >> 6) & 7, b = unit >> 9;
;         bf16* gp = Z2 + (size_t)(b * T + 64 * c + 16 * tt + fr) * NH2 + 3072 + h * 128 + 4 * fq;
;         unsigned long long ov[8], gv[8];
; #pragma unroll
;         for (int vt = 0; vt < 8; ++vt) { ov[vt] = OI[((size_t)(unit * 4 + tt) * 8 + vt) * 64 + lane]; gv[vt] = *(const unsigned long long*)(gp + 16 * vt); }
.LBB0_761:
	s_or_b64 exec, exec, s[0:1]
	s_mov_b64 s[4:5], 0
	v_mov_b32_e32 v0, v238
	s_waitcnt lgkmcnt(0)
	s_barrier
	v_readlane_b32 s9, v252, 0
	v_readfirstlane_b32 s0, v0
	s_mov_b32 s10, s29
	s_ashr_i32 s3, s0, 6
	s_nop 1
	s_and_b32 s12, s9, 7
	s_lshr_b32 s13, s9, 3
	s_lshl_b32 s13, s13, 3
	s_add_u32 s13, s13, s3
	s_lshr_b32 s14, s12, 1
	s_lshl_b32 s14, s14, 11
	s_add_u32 s100, s14, 0x7ff
	s_and_b32 s12, s12, 1
	s_lshl_b32 s12, s12, 7
	s_add_u32 s14, s14, s12
	s_and_b32 s12, s13, 127
	s_add_u32 s14, s14, s12
	s_lshr_b32 s12, s13, 7
	s_lshl_b32 s12, s12, 8
	s_add_u32 s14, s14, s12
	s_lshr_b32 s9, s14, 3
	s_and_b32 s3, s14, 7
	s_movk_i32 s10, 64
	s_lshl_b32 s11, s9, 3
	s_add_i32 s6, s11, s3
	s_cmp_gt_i32 s6, s100
	v_xor_b32_e32 v246, 16, v239
	v_and_b32_e32 v247, 64, v239
	v_xor_b32_e32 v245, 32, v239
	s_cbranch_scc1 .LBB0_765
	v_and_b32_e32 v18, 15, v0
	v_and_b32_e32 v3, 63, v0
	v_lshrrev_b32_e32 v0, 2, v0
	s_add_u32 s0, s78, s4
	v_readlane_b32 s7, v254, 28
	v_and_b32_e32 v2, 12, v0
	v_add_u32_e32 v0, 64, v247
	s_addc_u32 s1, s79, s5
	s_lshl_b32 s86, s7, 10
	v_readlane_b32 s16, v252, 19
	v_cmp_lt_i32_e32 vcc, v246, v0
	s_lshl_b32 s2, s10, 3
	s_lshl_b64 s[12:13], s[86:87], 2
	v_readlane_b32 s18, v252, 21
	v_cndmask_b32_e32 v4, v239, v246, vcc
	v_cmp_lt_i32_e32 vcc, v245, v0
	v_readlane_b32 s19, v252, 22
	s_add_u32 s12, s18, s12
	v_cndmask_b32_e32 v0, v239, v245, vcc
	s_addc_u32 s13, s19, s13
	v_lshlrev_b32_e32 v20, 2, v0
	v_lshlrev_b32_e32 v0, 2, v2
	v_lshl_add_u64 v[6:7], s[12:13], 0, v[0:1]
	s_lshl_b32 s7, s9, 4
	s_lshl_b32 s8, s3, 1
	s_lshl_b32 s9, s9, 7
	s_lshl_b32 s12, s3, 4
	s_add_i32 s7, s7, s8
	s_lshl_b32 s8, s10, 4
	s_add_i32 s9, s9, s12
	s_lshl_b32 s10, s10, 7
	s_ashr_i32 s13, s3, 31
	s_ashr_i32 s14, s11, 31
	s_add_u32 s12, s3, s11
	s_addc_u32 s13, s13, s14
	s_lshl_b64 s[12:13], s[12:13], 12
	s_add_u32 s3, s4, s12
	s_addc_u32 s5, s5, s13
	v_readlane_b32 s4, v254, 23
	s_add_u32 s4, s4, s3
	v_readlane_b32 s3, v254, 24
	v_lshlrev_b32_e32 v0, 3, v3
	s_addc_u32 s5, s3, s5
	s_ashr_i32 s3, s2, 31
	v_lshlrev_b32_e32 v19, 2, v4
	v_lshl_add_u64 v[8:9], s[4:5], 0, v[0:1]
	s_lshl_b64 s[4:5], s[2:3], 12
	v_lshlrev_b32_e32 v0, 1, v2
	v_readlane_b32 s17, v252, 20
	v_readlane_b32 s20, v252, 23
	v_readlane_b32 s21, v252, 24
	v_readlane_b32 s22, v252, 25
	v_readlane_b32 s23, v252, 26
	v_readlane_b32 s24, v252, 27
	v_readlane_b32 s25, v252, 28
	v_readlane_b32 s26, v252, 29
	v_readlane_b32 s27, v252, 30
	v_readlane_b32 s28, v252, 31
	v_readlane_b32 s29, v252, 32
	v_readlane_b32 s30, v252, 33
	v_readlane_b32 s31, v252, 34
.LBB0_763:
	global_load_dwordx2 v[16:17], v[8:9], off offset:-2048
	global_load_dwordx2 v[22:23], v[8:9], off offset:-1536
	global_load_dwordx2 v[24:25], v[8:9], off offset:-1024
	global_load_dwordx2 v[26:27], v[8:9], off offset:-512
	global_load_dwordx2 v[28:29], v[8:9], off
	global_load_dwordx2 v[30:31], v[8:9], off offset:512
	global_load_dwordx2 v[36:37], v[8:9], off offset:1024
	global_load_dwordx2 v[38:39], v[8:9], off offset:1536
	s_and_b32 s11, s9, 0xff0
	s_and_b32 s3, s7, 0xfffff000
	v_or_b32_e32 v2, s11, v18
	v_or_b32_e32 v2, s3, v2
	s_lshr_b32 s12, s6, 1
	v_ashrrev_i32_e32 v3, 31, v2
	s_and_b32 s11, s12, 0x380
	v_lshlrev_b64 v[2:3], 13, v[2:3]
	s_lshl_b32 s86, s11, 1
	v_lshl_add_u64 v[2:3], s[0:1], 0, v[2:3]
	v_lshl_add_u64 v[2:3], v[2:3], 0, s[86:87]
	s_lshl_b32 s86, s11, 2
	v_lshl_add_u64 v[14:15], v[2:3], 0, v[0:1]
	s_mov_b64 s[12:13], 0x6401800
	s_mov_b32 s3, 0x6401000
	v_lshl_add_u64 v[10:11], v[6:7], 0, s[86:87]
	v_lshl_add_u64 v[12:13], v[14:15], 0, s[12:13]
	v_add_co_u32_e32 v40, vcc, s3, v14
	global_load_dwordx4 v[2:5], v[10:11], off
	s_nop 0
	v_addc_co_u32_e32 v41, vcc, 0, v15, vcc
	global_load_dwordx2 v[14:15], v[12:13], off offset:32
	global_load_dwordx2 v[42:43], v[40:41], off offset:2048
	s_add_i32 s6, s6, s2
	s_add_i32 s7, s7, s8
	s_add_i32 s9, s9, s10
	v_lshl_add_u64 v[8:9], v[8:9], 0, s[4:5]
	s_cmp_gt_i32 s6, s100
	s_waitcnt vmcnt(10)
	v_and_b32_e32 v45, 0xffff0000, v16
	v_and_b32_e32 v47, 0xffff0000, v17
	s_waitcnt vmcnt(9)
	v_and_b32_e32 v49, 0xffff0000, v22
	v_and_b32_e32 v51, 0xffff0000, v23
	v_lshlrev_b32_e32 v44, 16, v16
	v_lshlrev_b32_e32 v46, 16, v17
	v_lshlrev_b32_e32 v48, 16, v22
	v_lshlrev_b32_e32 v50, 16, v23
	s_waitcnt vmcnt(8)
	v_and_b32_e32 v53, 0xffff0000, v24
	v_lshlrev_b32_e32 v54, 16, v25
	v_and_b32_e32 v55, 0xffff0000, v25
	s_waitcnt vmcnt(7)
	v_lshlrev_b32_e32 v56, 16, v26
	v_and_b32_e32 v57, 0xffff0000, v26
	v_lshlrev_b32_e32 v58, 16, v27
	v_and_b32_e32 v59, 0xffff0000, v27
	s_waitcnt vmcnt(6)
	v_lshlrev_b32_e32 v32, 16, v28
	v_and_b32_e32 v33, 0xffff0000, v28
	v_lshlrev_b32_e32 v34, 16, v29
	v_and_b32_e32 v35, 0xffff0000, v29
	s_waitcnt vmcnt(4)
	v_lshlrev_b32_e32 v26, 16, v36
	v_and_b32_e32 v27, 0xffff0000, v36
	v_lshlrev_b32_e32 v28, 16, v37
	v_and_b32_e32 v29, 0xffff0000, v37
	s_waitcnt vmcnt(3)
; DI unsigned pk2(float lo, float hi) { const bf2_t r = __builtin_convertvector((f32x2_t){lo, hi}, bf2_t); return __builtin_bit_cast(unsigned, r); }
; DI float lo16(unsigned u) { return __uint_as_float(u << 16); }
; DI float hi16(unsigned u) { return __uint_as_float(u & 0xffff0000u); }
; DI void hgrn3_phase(bf16* Z2, const unsigned long long* OI, const float* gain, int gw, int NGW, int lane) {
;     ...
;         float ss = 0.f;
; #pragma unroll
;         for (int vt = 0; vt < 8; ++vt) { const unsigned lo = (unsigned)ov[vt], hi = (unsigned)(ov[vt] >> 32); ss += (lo16(lo) * lo16(lo) + hi16(lo) * hi16(lo)) + (lo16(hi) * lo16(hi) + hi16(hi) * hi16(hi)); }
;         ss += __shfl_xor(ss, 16); ss += __shfl_xor(ss, 32);
;         const float rstd = __builtin_amdgcn_rsqf(ss * (1.0f / 128.0f) + EPS);
; #pragma unroll
;         for (int vt = 0; vt < 8; ++vt) { const f32x4 g4 = *(const f32x4*)(gain + h * 128 + 16 * vt + 4 * fq);
;             const unsigned lo = (unsigned)ov[vt], hi = (unsigned)(ov[vt] >> 32), glo = (unsigned)gv[vt], ghi = (unsigned)(gv[vt] >> 32);
;             const float of[4] = {lo16(lo), hi16(lo), lo16(hi), hi16(hi)}, gf[4] = {lo16(glo), hi16(glo), lo16(ghi), hi16(ghi)}; float r[4];
; #pragma unroll
;             for (int e = 0; e < 4; ++e) r[e] = of[e] * rstd * g4[e] * (gf[e] * __builtin_amdgcn_rcpf(1.0f + __expf(-gf[e])));
;             *(unsigned long long*)(gp + 16 * vt) = (unsigned long long)pk2(r[0], r[1]) | ((unsigned long long)pk2(r[2], r[3]) << 32); }
	v_lshlrev_b32_e32 v21, 16, v38
	v_and_b32_e32 v22, 0xffff0000, v38
	v_mul_f32_e32 v25, v45, v45
	v_mul_f32_e32 v36, v47, v47
	v_mul_f32_e32 v37, v49, v49
	v_mul_f32_e32 v38, v51, v51
	v_lshlrev_b32_e32 v52, 16, v24
	v_lshlrev_b32_e32 v23, 16, v39
	v_and_b32_e32 v24, 0xffff0000, v39
	v_mul_f32_e32 v39, v53, v53
	v_mul_f32_e32 v60, v55, v55
	v_fmac_f32_e32 v25, v44, v44
	v_fmac_f32_e32 v36, v46, v46
	v_fmac_f32_e32 v37, v48, v48
	v_fmac_f32_e32 v38, v50, v50
	v_mul_f32_e32 v61, v57, v57
	v_mul_f32_e32 v62, v59, v59
	v_fmac_f32_e32 v39, v52, v52
	v_fmac_f32_e32 v60, v54, v54
	v_add_f32_e32 v25, v25, v36
	v_add_f32_e32 v36, v37, v38
	v_lshlrev_b32_e32 v16, 16, v30
	v_and_b32_e32 v17, 0xffff0000, v30
	v_lshlrev_b32_e32 v30, 16, v31
	v_and_b32_e32 v31, 0xffff0000, v31
	v_mul_f32_e32 v63, v33, v33
	v_mul_f32_e32 v64, v35, v35
	v_fmac_f32_e32 v61, v56, v56
	v_fmac_f32_e32 v62, v58, v58
	v_add_f32_e32 v37, v39, v60
	v_add_f32_e32 v25, v25, v36
	v_mul_f32_e32 v65, v17, v17
	v_mul_f32_e32 v66, v31, v31
	v_fmac_f32_e32 v63, v32, v32
	v_fmac_f32_e32 v64, v34, v34
	v_add_f32_e32 v38, v61, v62
	v_add_f32_e32 v25, v25, v37
	v_mul_f32_e32 v67, v27, v27
	v_mul_f32_e32 v68, v29, v29
	v_fmac_f32_e32 v65, v16, v16
	v_fmac_f32_e32 v66, v30, v30
	v_add_f32_e32 v39, v63, v64
	v_add_f32_e32 v25, v25, v38
	v_mul_f32_e32 v69, v22, v22
	v_mul_f32_e32 v70, v24, v24
	v_fmac_f32_e32 v67, v26, v26
	v_fmac_f32_e32 v68, v28, v28
	v_add_f32_e32 v60, v65, v66
	v_add_f32_e32 v25, v25, v39
	v_fmac_f32_e32 v69, v21, v21
	v_fmac_f32_e32 v70, v23, v23
	v_add_f32_e32 v61, v67, v68
	v_add_f32_e32 v25, v25, v60
	v_add_f32_e32 v62, v69, v70
	v_add_f32_e32 v25, v25, v61
	v_add_f32_e32 v25, v25, v62
	ds_bpermute_b32 v62, v19, v25
	s_waitcnt vmcnt(0)
	v_lshlrev_b32_e32 v36, 16, v42
	v_and_b32_e32 v37, 0xffff0000, v42
	v_lshlrev_b32_e32 v38, 16, v43
	v_and_b32_e32 v39, 0xffff0000, v43
	s_waitcnt lgkmcnt(0)
	v_add_f32_e32 v25, v25, v62
	ds_bpermute_b32 v62, v20, v25
	v_mul_f32_e32 v42, 0xbfb8aa3b, v36
	v_mul_f32_e32 v43, 0xbfb8aa3b, v37
	v_mul_f32_e32 v60, 0xbfb8aa3b, v38
	v_mul_f32_e32 v61, 0xbfb8aa3b, v39
	v_exp_f32_e32 v42, v42
	v_exp_f32_e32 v43, v43
	v_exp_f32_e32 v60, v60
	v_exp_f32_e32 v61, v61
	s_waitcnt lgkmcnt(0)
	v_add_f32_e32 v25, v25, v62
	v_add_f32_e32 v42, 1.0, v42
	v_add_f32_e32 v43, 1.0, v43
	v_fmamk_f32 v25, v25, 0x3c000000, v240
	v_add_f32_e32 v60, 1.0, v60
	v_add_f32_e32 v61, 1.0, v61
	v_rcp_f32_e32 v42, v42
	v_rcp_f32_e32 v43, v43
	v_rsq_f32_e32 v25, v25
	v_rcp_f32_e32 v60, v60
	v_rcp_f32_e32 v61, v61
	v_mul_f32_e32 v36, v42, v36
	v_mul_f32_e32 v37, v43, v37
	v_mul_f32_e32 v42, v25, v44
	v_mul_f32_e32 v43, v25, v45
	v_mul_f32_e32 v44, v25, v46
	v_mul_f32_e32 v45, v25, v47
	v_mul_f32_e32 v38, v60, v38
	v_mul_f32_e32 v39, v61, v39
	v_mul_f32_e32 v2, v2, v42
	v_mul_f32_e32 v3, v3, v43
	v_mul_f32_e32 v4, v4, v44
	v_mul_f32_e32 v5, v5, v45
	v_mul_f32_e32 v2, v36, v2
	v_mul_f32_e32 v3, v37, v3
	v_mul_f32_e32 v4, v38, v4
	v_mul_f32_e32 v5, v39, v5
	v_cvt_pk_bf16_f32 v2, v2, v3
	v_cvt_pk_bf16_f32 v3, v4, v5
	global_store_dwordx2 v[40:41], v[2:3], off offset:2048
	global_load_dwordx4 v[2:5], v[10:11], off offset:64
	s_nop 0
	global_load_dwordx2 v[36:37], v[12:13], off offset:64
	v_lshlrev_b32_e32 v38, 16, v14
	v_and_b32_e32 v14, 0xffff0000, v14
	v_lshlrev_b32_e32 v39, 16, v15
	v_and_b32_e32 v15, 0xffff0000, v15
	v_mul_f32_e32 v40, 0xbfb8aa3b, v38
	v_mul_f32_e32 v41, 0xbfb8aa3b, v14
	v_mul_f32_e32 v42, 0xbfb8aa3b, v39
	v_mul_f32_e32 v43, 0xbfb8aa3b, v15
	v_exp_f32_e32 v40, v40
	v_exp_f32_e32 v41, v41
	v_exp_f32_e32 v42, v42
	v_exp_f32_e32 v43, v43
	v_add_f32_e32 v40, 1.0, v40
	v_add_f32_e32 v41, 1.0, v41
	v_add_f32_e32 v42, 1.0, v42
	v_add_f32_e32 v43, 1.0, v43
	v_rcp_f32_e32 v40, v40
	v_rcp_f32_e32 v41, v41
	v_rcp_f32_e32 v42, v42
	v_rcp_f32_e32 v43, v43
	v_mul_f32_e32 v38, v40, v38
	v_mul_f32_e32 v14, v41, v14
	v_mul_f32_e32 v39, v42, v39
	v_mul_f32_e32 v15, v43, v15
	v_mul_f32_e32 v40, v25, v48
	v_mul_f32_e32 v41, v25, v49
	v_mul_f32_e32 v42, v25, v50
	v_mul_f32_e32 v43, v25, v51
	v_mul_f32_e32 v32, v25, v32
	v_mul_f32_e32 v33, v25, v33
	v_mul_f32_e32 v34, v25, v34
	v_mul_f32_e32 v35, v25, v35
	v_mul_f32_e32 v16, v25, v16
	v_mul_f32_e32 v17, v25, v17
	v_mul_f32_e32 v30, v25, v30
	v_mul_f32_e32 v31, v25, v31
	v_mul_f32_e32 v26, v25, v26
	v_mul_f32_e32 v27, v25, v27
	v_mul_f32_e32 v28, v25, v28
	v_mul_f32_e32 v29, v25, v29
	s_waitcnt vmcnt(1)
	v_mul_f32_e32 v2, v2, v40
	v_mul_f32_e32 v3, v3, v41
	v_mul_f32_e32 v4, v4, v42
	v_mul_f32_e32 v5, v5, v43
	v_mul_f32_e32 v2, v38, v2
	v_mul_f32_e32 v3, v14, v3
	v_mul_f32_e32 v4, v39, v4
	v_mul_f32_e32 v5, v15, v5
	v_cvt_pk_bf16_f32 v2, v2, v3
	v_cvt_pk_bf16_f32 v3, v4, v5
	global_store_dwordx2 v[12:13], v[2:3], off offset:32
	global_load_dwordx4 v[2:5], v[10:11], off offset:128
	s_nop 0
	global_load_dwordx2 v[38:39], v[12:13], off offset:96
	s_waitcnt vmcnt(3)
	v_lshlrev_b32_e32 v14, 16, v36
	v_and_b32_e32 v15, 0xffff0000, v36
	v_lshlrev_b32_e32 v36, 16, v37
	v_and_b32_e32 v37, 0xffff0000, v37
	v_mul_f32_e32 v40, 0xbfb8aa3b, v14
	v_mul_f32_e32 v41, 0xbfb8aa3b, v15
	v_mul_f32_e32 v42, 0xbfb8aa3b, v36
	v_mul_f32_e32 v43, 0xbfb8aa3b, v37
	v_exp_f32_e32 v40, v40
	v_exp_f32_e32 v41, v41
	v_exp_f32_e32 v42, v42
	v_exp_f32_e32 v43, v43
	v_add_f32_e32 v40, 1.0, v40
	v_add_f32_e32 v41, 1.0, v41
	v_add_f32_e32 v42, 1.0, v42
	v_add_f32_e32 v43, 1.0, v43
	v_rcp_f32_e32 v40, v40
	v_rcp_f32_e32 v41, v41
	v_rcp_f32_e32 v42, v42
	v_rcp_f32_e32 v43, v43
	v_mul_f32_e32 v14, v40, v14
	v_mul_f32_e32 v15, v41, v15
	v_mul_f32_e32 v36, v42, v36
	v_mul_f32_e32 v37, v43, v37
	v_mul_f32_e32 v40, v25, v52
	v_mul_f32_e32 v41, v25, v53
	v_mul_f32_e32 v42, v25, v54
	v_mul_f32_e32 v43, v25, v55
	s_waitcnt vmcnt(1)
; DI unsigned pk2(float lo, float hi) { const bf2_t r = __builtin_convertvector((f32x2_t){lo, hi}, bf2_t); return __builtin_bit_cast(unsigned, r); }
; DI float lo16(unsigned u) { return __uint_as_float(u << 16); }
; DI float hi16(unsigned u) { return __uint_as_float(u & 0xffff0000u); }
; DI void hgrn3_phase(bf16* Z2, const unsigned long long* OI, const float* gain, int gw, int NGW, int lane) {
;     ...
; #pragma unroll
;         for (int vt = 0; vt < 8; ++vt) { const f32x4 g4 = *(const f32x4*)(gain + h * 128 + 16 * vt + 4 * fq);
;             const unsigned lo = (unsigned)ov[vt], hi = (unsigned)(ov[vt] >> 32), glo = (unsigned)gv[vt], ghi = (unsigned)(gv[vt] >> 32);
;             const float of[4] = {lo16(lo), hi16(lo), lo16(hi), hi16(hi)}, gf[4] = {lo16(glo), hi16(glo), lo16(ghi), hi16(ghi)}; float r[4];
; #pragma unroll
;             for (int e = 0; e < 4; ++e) r[e] = of[e] * rstd * g4[e] * (gf[e] * __builtin_amdgcn_rcpf(1.0f + __expf(-gf[e])));
;             *(unsigned long long*)(gp + 16 * vt) = (unsigned long long)pk2(r[0], r[1]) | ((unsigned long long)pk2(r[2], r[3]) << 32); }
;     }
	v_mul_f32_e32 v2, v2, v40
	v_mul_f32_e32 v3, v3, v41
	v_mul_f32_e32 v4, v4, v42
	v_mul_f32_e32 v5, v5, v43
	v_mul_f32_e32 v2, v14, v2
	v_mul_f32_e32 v3, v15, v3
	v_mul_f32_e32 v4, v36, v4
	v_mul_f32_e32 v5, v37, v5
	v_cvt_pk_bf16_f32 v2, v2, v3
	v_cvt_pk_bf16_f32 v3, v4, v5
	global_store_dwordx2 v[12:13], v[2:3], off offset:64
	global_load_dwordx4 v[2:5], v[10:11], off offset:192
	s_nop 0
	global_load_dwordx2 v[14:15], v[12:13], off offset:128
	s_waitcnt vmcnt(3)
	v_lshlrev_b32_e32 v36, 16, v38
	v_and_b32_e32 v37, 0xffff0000, v38
	v_lshlrev_b32_e32 v38, 16, v39
	v_and_b32_e32 v39, 0xffff0000, v39
	v_mul_f32_e32 v40, 0xbfb8aa3b, v36
	v_mul_f32_e32 v41, 0xbfb8aa3b, v37
	v_mul_f32_e32 v42, 0xbfb8aa3b, v38
	v_mul_f32_e32 v43, 0xbfb8aa3b, v39
	v_exp_f32_e32 v40, v40
	v_exp_f32_e32 v41, v41
	v_exp_f32_e32 v42, v42
	v_exp_f32_e32 v43, v43
	v_add_f32_e32 v40, 1.0, v40
	v_add_f32_e32 v41, 1.0, v41
	v_add_f32_e32 v42, 1.0, v42
	v_add_f32_e32 v43, 1.0, v43
	v_rcp_f32_e32 v40, v40
	v_rcp_f32_e32 v41, v41
	v_rcp_f32_e32 v42, v42
	v_rcp_f32_e32 v43, v43
	v_mul_f32_e32 v36, v40, v36
	v_mul_f32_e32 v37, v41, v37
	v_mul_f32_e32 v38, v42, v38
	v_mul_f32_e32 v39, v43, v39
	v_mul_f32_e32 v40, v25, v56
	v_mul_f32_e32 v41, v25, v57
	v_mul_f32_e32 v42, v25, v58
	v_mul_f32_e32 v43, v25, v59
	s_waitcnt vmcnt(1)
	v_mul_f32_e32 v2, v2, v40
	v_mul_f32_e32 v3, v3, v41
	v_mul_f32_e32 v4, v4, v42
	v_mul_f32_e32 v5, v5, v43
	v_mul_f32_e32 v2, v36, v2
	v_mul_f32_e32 v3, v37, v3
	v_mul_f32_e32 v4, v38, v4
	v_mul_f32_e32 v5, v39, v5
	v_cvt_pk_bf16_f32 v2, v2, v3
	v_cvt_pk_bf16_f32 v3, v4, v5
	global_store_dwordx2 v[12:13], v[2:3], off offset:96
	global_load_dwordx4 v[2:5], v[10:11], off offset:256
	s_nop 0
	global_load_dwordx2 v[36:37], v[12:13], off offset:160
	s_waitcnt vmcnt(3)
	v_lshlrev_b32_e32 v38, 16, v14
	v_and_b32_e32 v14, 0xffff0000, v14
	v_lshlrev_b32_e32 v39, 16, v15
	v_and_b32_e32 v15, 0xffff0000, v15
	v_mul_f32_e32 v40, 0xbfb8aa3b, v38
	v_mul_f32_e32 v41, 0xbfb8aa3b, v14
	v_mul_f32_e32 v42, 0xbfb8aa3b, v39
	v_mul_f32_e32 v43, 0xbfb8aa3b, v15
	v_exp_f32_e32 v40, v40
	v_exp_f32_e32 v41, v41
	v_exp_f32_e32 v42, v42
	v_exp_f32_e32 v43, v43
	v_add_f32_e32 v40, 1.0, v40
	v_add_f32_e32 v41, 1.0, v41
	v_add_f32_e32 v42, 1.0, v42
	v_add_f32_e32 v43, 1.0, v43
	v_rcp_f32_e32 v40, v40
	v_rcp_f32_e32 v41, v41
	v_rcp_f32_e32 v42, v42
	v_rcp_f32_e32 v43, v43
	v_mul_f32_e32 v38, v40, v38
	v_mul_f32_e32 v14, v41, v14
	v_mul_f32_e32 v39, v42, v39
	v_mul_f32_e32 v15, v43, v15
	s_waitcnt vmcnt(1)
	v_mul_f32_e32 v2, v2, v32
	v_mul_f32_e32 v3, v3, v33
	v_mul_f32_e32 v4, v4, v34
	v_mul_f32_e32 v5, v5, v35
	v_mul_f32_e32 v2, v38, v2
	v_mul_f32_e32 v3, v14, v3
	v_mul_f32_e32 v4, v39, v4
	v_mul_f32_e32 v5, v15, v5
	v_cvt_pk_bf16_f32 v2, v2, v3
	v_cvt_pk_bf16_f32 v3, v4, v5
	global_store_dwordx2 v[12:13], v[2:3], off offset:128
	global_load_dwordx4 v[2:5], v[10:11], off offset:320
	s_nop 0
	global_load_dwordx2 v[14:15], v[12:13], off offset:192
	s_waitcnt vmcnt(3)
	v_lshlrev_b32_e32 v32, 16, v36
	v_and_b32_e32 v33, 0xffff0000, v36
	v_lshlrev_b32_e32 v34, 16, v37
	v_and_b32_e32 v35, 0xffff0000, v37
	v_mul_f32_e32 v36, 0xbfb8aa3b, v32
	v_mul_f32_e32 v37, 0xbfb8aa3b, v33
	v_mul_f32_e32 v38, 0xbfb8aa3b, v34
	v_mul_f32_e32 v39, 0xbfb8aa3b, v35
	v_exp_f32_e32 v36, v36
	v_exp_f32_e32 v37, v37
	v_exp_f32_e32 v38, v38
	v_exp_f32_e32 v39, v39
	v_add_f32_e32 v36, 1.0, v36
	v_add_f32_e32 v37, 1.0, v37
	v_add_f32_e32 v38, 1.0, v38
	v_add_f32_e32 v39, 1.0, v39
	v_rcp_f32_e32 v36, v36
	v_rcp_f32_e32 v37, v37
	v_rcp_f32_e32 v38, v38
	v_rcp_f32_e32 v39, v39
	v_mul_f32_e32 v32, v36, v32
	v_mul_f32_e32 v33, v37, v33
	v_mul_f32_e32 v34, v38, v34
	v_mul_f32_e32 v35, v39, v35
	s_waitcnt vmcnt(1)
	v_mul_f32_e32 v2, v16, v2
	v_mul_f32_e32 v3, v17, v3
	v_mul_f32_e32 v4, v30, v4
	v_mul_f32_e32 v5, v31, v5
	v_mul_f32_e32 v2, v32, v2
	v_mul_f32_e32 v3, v33, v3
	v_mul_f32_e32 v4, v34, v4
	v_mul_f32_e32 v5, v35, v5
	v_cvt_pk_bf16_f32 v2, v2, v3
	v_cvt_pk_bf16_f32 v3, v4, v5
	global_store_dwordx2 v[12:13], v[2:3], off offset:160
	global_load_dwordx4 v[2:5], v[10:11], off offset:384
	s_nop 0
	global_load_dwordx2 v[16:17], v[12:13], off offset:224
	s_waitcnt vmcnt(3)
	v_lshlrev_b32_e32 v30, 16, v14
	v_and_b32_e32 v14, 0xffff0000, v14
	v_lshlrev_b32_e32 v31, 16, v15
	v_and_b32_e32 v15, 0xffff0000, v15
	v_mul_f32_e32 v32, 0xbfb8aa3b, v30
	v_mul_f32_e32 v33, 0xbfb8aa3b, v14
	v_mul_f32_e32 v34, 0xbfb8aa3b, v31
	v_mul_f32_e32 v35, 0xbfb8aa3b, v15
	v_exp_f32_e32 v32, v32
	v_exp_f32_e32 v33, v33
	v_exp_f32_e32 v34, v34
	v_exp_f32_e32 v35, v35
	v_add_f32_e32 v32, 1.0, v32
	v_add_f32_e32 v33, 1.0, v33
	v_add_f32_e32 v34, 1.0, v34
	v_add_f32_e32 v35, 1.0, v35
	v_rcp_f32_e32 v32, v32
	v_rcp_f32_e32 v33, v33
	v_rcp_f32_e32 v34, v34
	v_rcp_f32_e32 v35, v35
	v_mul_f32_e32 v30, v32, v30
	v_mul_f32_e32 v14, v33, v14
	v_mul_f32_e32 v31, v34, v31
	v_mul_f32_e32 v15, v35, v15
	s_waitcnt vmcnt(1)
	v_mul_f32_e32 v2, v26, v2
	v_mul_f32_e32 v3, v27, v3
	v_mul_f32_e32 v4, v28, v4
	v_mul_f32_e32 v5, v29, v5
	v_mul_f32_e32 v2, v30, v2
	v_mul_f32_e32 v3, v14, v3
	v_mul_f32_e32 v4, v31, v4
	v_mul_f32_e32 v5, v15, v5
	v_cvt_pk_bf16_f32 v2, v2, v3
	v_cvt_pk_bf16_f32 v3, v4, v5
	global_store_dwordx2 v[12:13], v[2:3], off offset:192
	global_load_dwordx4 v[2:5], v[10:11], off offset:448
	s_waitcnt vmcnt(2)
	v_lshlrev_b32_e32 v10, 16, v16
	v_and_b32_e32 v11, 0xffff0000, v16
	v_lshlrev_b32_e32 v14, 16, v17
	v_and_b32_e32 v15, 0xffff0000, v17
	v_mul_f32_e32 v16, 0xbfb8aa3b, v10
	v_mul_f32_e32 v17, 0xbfb8aa3b, v11
	v_mul_f32_e32 v26, 0xbfb8aa3b, v14
	v_mul_f32_e32 v27, 0xbfb8aa3b, v15
	v_exp_f32_e32 v16, v16
	v_exp_f32_e32 v17, v17
	v_exp_f32_e32 v26, v26
	v_exp_f32_e32 v27, v27
	v_add_f32_e32 v16, 1.0, v16
	v_add_f32_e32 v17, 1.0, v17
	v_add_f32_e32 v26, 1.0, v26
	v_add_f32_e32 v27, 1.0, v27
	v_rcp_f32_e32 v16, v16
	v_rcp_f32_e32 v17, v17
	v_rcp_f32_e32 v26, v26
	v_rcp_f32_e32 v27, v27
	v_mul_f32_e32 v10, v16, v10
	v_mul_f32_e32 v11, v17, v11
	v_mul_f32_e32 v16, v25, v21
	v_mul_f32_e32 v17, v25, v22
	v_mul_f32_e32 v21, v25, v23
	v_mul_f32_e32 v22, v25, v24
	v_mul_f32_e32 v14, v26, v14
	v_mul_f32_e32 v15, v27, v15
	s_waitcnt vmcnt(0)
	v_mul_f32_e32 v2, v16, v2
	v_mul_f32_e32 v3, v17, v3
	v_mul_f32_e32 v4, v21, v4
	v_mul_f32_e32 v5, v22, v5
	v_mul_f32_e32 v2, v10, v2
	v_mul_f32_e32 v3, v11, v3
	v_mul_f32_e32 v4, v14, v4
	v_mul_f32_e32 v5, v15, v5
	v_cvt_pk_bf16_f32 v2, v2, v3
	v_cvt_pk_bf16_f32 v3, v4, v5
	global_store_dwordx2 v[12:13], v[2:3], off offset:224
	s_cbranch_scc0 .LBB0_763
	v_readlane_b32 s30, v254, 31
	v_readlane_b32 s26, v254, 33
	v_readlane_b32 s29, v252, 39
	v_readlane_b32 s31, v254, 32
	v_readlane_b32 s27, v254, 34
